# v46 + prompt attention: Q fragments of the next item prefetched one item ahead (into spare VGPRs) together with its K/V rows
# baseline (speedup 1.0000x reference)
; #define LAS __attribute__((address_space(3)))
; __device__ __forceinline__ void attn_mfma_phase(LAS unsigned char* lds, const bf16* QKVb, bf16* OPART, float2* ML, int tid, int wave, int lane) {
;     ...
;     const int i = lane & 31, hh = lane >> 5, i16 = lane & 15, tq = i16 >> 2, tp = i16 & 3, blk = (lane >> 4) & 1;
;     v4u pk[6], pv[6];
;     auto decode = [](int item, int& h, int& b, int& r, int& bk) { h = item / 192; const int w = item % 192;
;         if (w < 64) { b = 0; r = 0; bk = w; } else if (w < 128) { b = 1; r = (w - 64) >> 4; bk = (w - 64) & 15; } else { b = 2; r = (w - 128) >> 2; bk = (w - 128) & 3; } };
;     auto issue = [&](int item) { int h, b, r, bk; decode(item, h, b, r, bk); const int d = 1 << (2 * b), L0 = bk * 256;
; #pragma unroll
;         for (int c = 0; c < 6; ++c) { const int e = tid + NTHR * c, j = e >> 3, ch = e & 7, l = L0 - 128 + j;
;             if (l >= 0) { const bf16* src = QKVb + (size_t)(l * d + r) * INW + h * 64 + 8 * ch; pk[c] = *(const v4u*)(src + C_KA); pv[c] = *(const v4u*)(src + C_VA); } } };
;     if ((int)blockIdx.x < 1536) issue(blockIdx.x);
;     for (int item = blockIdx.x; item < 1536; item += gridDim.x) {
;         int h, b, r, bk; decode(item, h, b, r, bk);
;         const int d = 1 << (2 * b), L0 = bk * 256;
; #pragma unroll
;         for (int c = 0; c < 6; ++c) { const int e = tid + NTHR * c, j = e >> 3, ch = e & 7;
;             *(LAS v4u*)(kimg + j * RSK + 16 * ch) = pk[c]; *(LAS v4u*)(vimg + j * RSV + 16 * ch) = pv[c]; }
;         const int l0 = L0 + 32 * wave;
;         const int tok_q = (l0 + i) * d + r;
;         const bf16* qp = QKVb + (size_t)tok_q * INW + C_QA + h * 64 + 8 * hh;
;         bf16x8 qf[4];
; #pragma unroll
;         for (int ks = 0; ks < 4; ++ks) qf[ks] = *(const bf16x8*)(qp + 16 * ks);
;         __syncthreads();
;         if (item + (int)gridDim.x < 1536) issue(item + gridDim.x);
;         f32x16 o0, o1;
; #pragma unroll
;         for (int e = 0; e < 16; ++e) { o0[e] = 0.f; o1[e] = 0.f; }
;         float m = -1e30f, l = 0.f;
;         const int kt0 = l0 >= 128 ? 0 : ((128 - l0) >> 5);
;         for (int kt = kt0; kt < 5; ++kt) {
;             const int jb = 32 * wave + 32 * kt;
;             const LAS unsigned char* kp = kimg + (jb + i) * RSK + 16 * hh;
;             f32x16 s;
; #pragma unroll
;             for (int e = 0; e < 16; ++e) s[e] = 0.f;
; #pragma unroll
.LBB0_1008:
	s_add_u32 s74, s90, 0x29b00000
	v_writelane_b32 v254, s72, 55
	s_addc_u32 s75, s91, 0
	v_lshrrev_b32_e32 v191, 5, v162
	v_writelane_b32 v254, s73, 56
	s_add_u32 s58, s90, 0x2cc00000
	v_and_b32_e32 v133, 31, v0
	v_bfe_u32 v192, v0, 2, 2
	s_addc_u32 s59, s91, 0
	s_andn2_b64 vcc, exec, s[0:1]
	v_lshlrev_b32_e32 v140, 3, v191
	v_lshlrev_b32_e32 v136, 4, v191
	v_lshlrev_b32_e32 v138, 2, v191
	v_lshlrev_b32_e32 v193, 1, v0
	v_writelane_b32 v254, s52, 63
	s_nop 1
	v_writelane_b32 v255, s53, 0
	s_cbranch_vccnz .LBB0_1055
	v_and_b32_e32 v2, 0x70, v187
	v_writelane_b32 v255, s24, 1
	v_add_u32_e32 v135, 0, v2
	v_or_b32_e32 v2, 0x200, v0
	v_writelane_b32 v255, s25, 2
	v_lshrrev_b32_e32 v145, 3, v2
	v_or_b32_e32 v2, 0x600, v0
	v_writelane_b32 v255, s36, 3
	v_lshrrev_b32_e32 v151, 3, v2
	v_or_b32_e32 v2, 0xa00, v0
	v_writelane_b32 v255, s37, 4
	v_lshrrev_b32_e32 v153, 3, v2
	v_mbcnt_lo_u32_b32 v2, -1, 0
	v_writelane_b32 v255, s58, 5
	v_mbcnt_hi_u32_b32 v2, -1, v2
	v_and_b32_e32 v4, 64, v2
	v_writelane_b32 v255, s59, 6
	v_writelane_b32 v255, s56, 7
	v_xor_b32_e32 v3, 32, v2
	v_add_u32_e32 v4, 64, v4
	v_writelane_b32 v255, s57, 8
	v_lshrrev_b32_e32 v137, 3, v0
	v_cmp_lt_i32_e32 vcc, v3, v4
	v_writelane_b32 v255, s54, 9
	v_readlane_b32 s0, v254, 34
	v_cndmask_b32_e32 v2, v2, v3, vcc
	s_movk_i32 s1, 0xc0
	v_mul_u32_u24_e32 v155, 0xc0, v137
	v_mov_b32_e32 v5, 0x6000
	v_or_b32_e32 v11, 2, v138
	v_writelane_b32 v255, s55, 10
	s_lshl_b32 s2, s0, 5
	v_lshlrev_b32_e32 v154, 2, v2
	s_movk_i32 s0, 0x90
	v_mul_u32_u24_e32 v2, 0x90, v137
	v_mul_u32_u24_e32 v3, 0x90, v145
	v_mul_u32_u24_e32 v4, 0xc0, v145
	v_mad_u32_u24 v5, v137, s1, v5
	v_mul_u32_u24_e32 v6, 0x90, v151
	v_mul_u32_u24_e32 v7, 0xc0, v151
	v_or_b32_e32 v8, 0xc000, v155
	v_mul_u32_u24_e32 v9, 0x90, v153
	v_mul_u32_u24_e32 v10, 0xc0, v153
	v_cmp_gt_u32_e64 s[10:11], v11, v133
	v_or_b32_e32 v12, 3, v138
	v_or_b32_e32 v13, 8, v138
	v_or_b32_e32 v14, 9, v138
	v_or_b32_e32 v15, 10, v138
	v_or_b32_e32 v16, 11, v138
	v_or_b32_e32 v17, 16, v138
	s_waitcnt vmcnt(2)
	v_or_b32_e32 v18, 17, v138
	v_or_b32_e32 v19, 18, v138
	v_or_b32_e32 v20, 19, v138
	v_or_b32_e32 v21, 24, v138
	v_or_b32_e32 v22, 25, v138
	v_or_b32_e32 v23, 26, v138
	v_or_b32_e32 v24, 27, v138
	v_or_b32_e32 v25, 1, v138
	v_cmp_lt_u32_e64 s[42:43], v11, v133
	v_lshlrev_b32_e32 v11, 3, v141
	v_writelane_b32 v255, s69, 11
	v_mov_b32_e32 v143, 0
	v_and_b32_e32 v144, 56, v139
	v_or_b32_e32 v150, 0x80, v137
	v_or_b32_e32 v152, 0x100, v137
	v_cmp_gt_u32_e64 s[4:5], 32, v162
	v_cmp_gt_u32_e64 s[6:7], v138, v133
	v_cmp_lt_u32_e64 s[8:9], v138, v133
	v_cmp_gt_u32_e64 s[12:13], v12, v133
	v_cmp_gt_u32_e64 s[14:15], v13, v133
	v_cmp_gt_u32_e64 s[16:17], v14, v133
	v_cmp_gt_u32_e64 s[18:19], v15, v133
	v_cmp_gt_u32_e64 s[20:21], v16, v133
	v_cmp_gt_u32_e64 s[22:23], v17, v133
	v_cmp_gt_u32_e64 s[24:25], v18, v133
	v_cmp_gt_u32_e64 s[26:27], v19, v133
	v_cmp_gt_u32_e64 s[28:29], v20, v133
	v_cmp_gt_u32_e64 s[30:31], v21, v133
	v_cmp_gt_u32_e64 s[34:35], v22, v133
	v_cmp_gt_u32_e64 s[36:37], v23, v133
	v_cmp_gt_u32_e64 s[38:39], v24, v133
	v_cmp_lt_u32_e64 s[40:41], v25, v133
	v_cmp_lt_u32_e64 s[44:45], v12, v133
	v_cmp_lt_u32_e64 s[46:47], v13, v133
	v_cmp_lt_u32_e64 s[48:49], v14, v133
	v_cmp_lt_u32_e64 s[50:51], v15, v133
	v_cmp_lt_u32_e64 s[52:53], v16, v133
	v_cmp_lt_u32_e64 s[54:55], v17, v133
	v_cmp_lt_u32_e64 s[56:57], v18, v133
	v_cmp_lt_u32_e64 s[58:59], v19, v133
	v_cmp_lt_u32_e64 s[60:61], v20, v133
	v_cmp_lt_u32_e64 s[62:63], v21, v133
	v_cmp_lt_u32_e64 s[64:65], v22, v133
	v_cmp_lt_u32_e64 s[66:67], v23, v133
	v_cmp_lt_u32_e64 s[68:69], v24, v133
	v_and_or_b32 v156, v193, 32, v11
	v_or_b32_e32 v157, v138, v192
	v_mad_u32_u24 v158, v133, s0, v136
	v_add_u32_e32 v159, v135, v2
	v_add_u32_e32 v160, v135, v3
	v_add_u32_e32 v161, v135, v4
	v_add_u32_e32 v168, v135, v5
	v_add_u32_e32 v169, v135, v6
	v_add_u32_e32 v170, v135, v7
	v_add_u32_e32 v171, v135, v8
	v_add_u32_e32 v172, v135, v9
	v_add_u32_e32 v173, v135, v10
	s_movk_i32 s3, 0x1800
	v_lshlrev_b32_e32 v142, 1, v140
	v_lshlrev_b32_e32 v146, 1, v138
	v_mov_b32_e32 v174, 0xf149f2ca
	s_mov_b32 s101, 0
	s_branch .LBB0_1011

; #define LAS __attribute__((address_space(3)))
; __device__ __forceinline__ void attn_mfma_phase(LAS unsigned char* lds, const bf16* QKVb, bf16* OPART, float2* ML, int tid, int wave, int lane) {
;     ...
;         int h, b, r, bk; decode(item, h, b, r, bk);
;         const int d = 1 << (2 * b), L0 = bk * 256;
; #pragma unroll
;         for (int c = 0; c < 6; ++c) { const int e = tid + NTHR * c, j = e >> 3, ch = e & 7;
;             *(LAS v4u*)(kimg + j * RSK + 16 * ch) = pk[c]; *(LAS v4u*)(vimg + j * RSV + 16 * ch) = pv[c]; }
;         const int l0 = L0 + 32 * wave;
;         const int tok_q = (l0 + i) * d + r;
;         const bf16* qp = QKVb + (size_t)tok_q * INW + C_QA + h * 64 + 8 * hh;
;         bf16x8 qf[4];
; #pragma unroll
;         for (int ks = 0; ks < 4; ++ks) qf[ks] = *(const bf16x8*)(qp + 16 * ks);
;         __syncthreads();
;         if (item + (int)gridDim.x < 1536) issue(item + gridDim.x);
.LBB0_1018:
	s_lshl_b32 s87, s84, 8
	s_add_i32 s87, s87, s2
	s_lshl_b32 s70, s1, 1
	v_or_b32_e32 v2, s87, v133
	v_lshlrev_b32_e32 v2, s70, v2
	v_readlane_b32 s70, v254, 55
	v_readlane_b32 s71, v254, 56
	v_add_u32_e32 v148, s33, v2
	s_lshl_b32 s94, s0, 6
	v_mov_b64_e32 v[2:3], s[70:71]
	v_mad_i64_i32 v[2:3], s[70:71], v148, s3, v[2:3]
	s_ashr_i32 s95, s94, 31
	v_lshl_add_u64 v[2:3], s[94:95], 1, v[2:3]
	v_lshl_add_u64 v[2:3], v[2:3], 0, v[142:143]
	s_cmp_lg_u32 s101, 0
	s_cbranch_scc1 .Lq_skip
	global_load_dwordx4 v[114:117], v[2:3], off
	global_load_dwordx4 v[118:121], v[2:3], off offset:32
	global_load_dwordx4 v[122:125], v[2:3], off offset:64
	global_load_dwordx4 v[126:129], v[2:3], off offset:96
.Lq_skip:
	s_movk_i32 s33, 128
	s_add_i32 s86, s86, s33
	s_cmpk_gt_i32 s86, 0x5ff
	s_cselect_b64 s[72:73], -1, 0
	v_add_u32_e32 v2, v135, v155
	s_and_b64 vcc, exec, s[72:73]
	s_waitcnt vmcnt(5)
	ds_write_b128 v159, v[70:73]
	s_waitcnt vmcnt(4)
	ds_write_b128 v2, v[66:69] offset:55296
	ds_write_b128 v160, v[78:81]
	ds_write_b128 v161, v[74:77] offset:55296
	ds_write_b128 v159, v[86:89] offset:18432
	ds_write_b128 v168, v[82:85] offset:55296
	ds_write_b128 v169, v[94:97]
	ds_write_b128 v170, v[90:93] offset:55296
	ds_write_b128 v159, v[102:105] offset:36864
	ds_write_b128 v171, v[98:101] offset:55296
	ds_write_b128 v172, v[110:113]
	ds_write_b128 v173, v[106:109] offset:55296
	s_waitcnt lgkmcnt(0)
	s_barrier
	s_waitcnt vmcnt(0)
	s_cmp_eq_u32 s101, 0
	s_cbranch_scc1 .Lq_first
	v_mov_b64_e32 v[114:115], v[202:203]
	v_mov_b64_e32 v[116:117], v[204:205]
	v_mov_b64_e32 v[118:119], v[206:207]
	v_mov_b64_e32 v[120:121], v[208:209]
	v_mov_b64_e32 v[122:123], v[210:211]
	v_mov_b64_e32 v[124:125], v[212:213]
	v_mov_b64_e32 v[126:127], v[214:215]
	v_mov_b64_e32 v[128:129], v[216:217]
.Lq_first:
	s_mov_b32 s101, 1
	s_cbranch_vccnz .LBB0_1039
	s_mul_hi_i32 s33, s86, 0x2aaaaaab
	s_lshr_b32 s70, s33, 31
	s_ashr_i32 s96, s33, 5
	s_add_i32 s96, s96, s70
	s_mul_i32 s33, s96, 0xc0
	s_sub_i32 s70, s86, s33
	s_cmp_lt_i32 s70, 64
	s_mov_b32 s84, 0
	s_cbranch_scc1 .LBB0_1025
	s_cmpk_gt_u32 s70, 0x7f
	s_mov_b64 s[92:93], -1
	s_cbranch_scc0 .LBB0_1022
	s_add_i32 s33, s70, 0xffffff80
	s_lshr_b32 s84, s33, 2
	s_and_b32 s33, s70, 3
	s_mov_b64 s[92:93], 0

; __device__ __forceinline__ void attn_mfma_phase(LAS unsigned char* lds, const bf16* QKVb, bf16* OPART, float2* ML, int tid, int wave, int lane) {
;     ...
;     auto issue = [&](int item) { int h, b, r, bk; decode(item, h, b, r, bk); const int d = 1 << (2 * b), L0 = bk * 256;
; #pragma unroll
;         for (int c = 0; c < 6; ++c) { const int e = tid + NTHR * c, j = e >> 3, ch = e & 7, l = L0 - 128 + j;
;             if (l >= 0) { const bf16* src = QKVb + (size_t)(l * d + r) * INW + h * 64 + 8 * ch; pk[c] = *(const v4u*)(src + C_KA); pv[c] = *(const v4u*)(src + C_VA); } } };
;     ...
;         const int l0 = L0 + 32 * wave;
;         const int tok_q = (l0 + i) * d + r;
;         const bf16* qp = QKVb + (size_t)tok_q * INW + C_QA + h * 64 + 8 * hh;
;         bf16x8 qf[4];
; #pragma unroll
;         for (int ks = 0; ks < 4; ++ks) qf[ks] = *(const bf16x8*)(qp + 16 * ks);
.LBB0_1038:
	s_or_b64 exec, exec, s[92:93]
	s_addk_i32 s33, 0x80
	s_add_i32 s33, s33, s2
	v_add_u32_e32 v2, s33, v133
	v_lshlrev_b32_e32 v2, s85, v2
	v_add_u32_e32 v2, s84, v2
	v_readlane_b32 s70, v254, 55
	v_readlane_b32 s71, v254, 56
	s_nop 1
	v_mov_b64_e32 v[4:5], s[70:71]
	v_mad_i64_i32 v[4:5], s[70:71], v2, s3, v[4:5]
	v_lshl_add_u64 v[4:5], s[96:97], 1, v[4:5]
	v_lshl_add_u64 v[4:5], v[4:5], 0, v[142:143]
	global_load_dwordx4 v[202:205], v[4:5], off
	global_load_dwordx4 v[206:209], v[4:5], off offset:32
	global_load_dwordx4 v[210:213], v[4:5], off offset:64
	global_load_dwordx4 v[214:217], v[4:5], off offset:96
